# final3 + FoX G-row prefetch across key steps (gpre2)
# baseline (speedup 1.0000x reference)
; #define LAS __attribute__((address_space(3)))
; __device__ __forceinline__ unsigned pk2(float lo, float hi) { f32x2_t v = {lo, hi}; bf16x2_t b = __builtin_convertvector(v, bf16x2_t); return __builtin_bit_cast(unsigned, b); }
; __device__ __forceinline__ float bf_lo(unsigned w) { return __uint_as_float(w << 16); }
; __device__ __forceinline__ float bf_hi(unsigned w) { return __uint_as_float(w & 0xffff0000u); }
; __device__ __forceinline__ void finish(St& S, bf16_t* Yrow, const bf16_t* __restrict__ Grow, LAS unsigned char* ostage, int lane) {
;     const int r32 = lane & 31, hi = lane >> 5;
;     const float inv = 1.0f / xhalf_sum(S.l);
; #pragma unroll
;     for (int db = 0; db < 2; ++db)
; #pragma unroll
;         for (int g = 0; g < 4; ++g) {
;             f32x4 v;
; #pragma unroll
;             for (int e2 = 0; e2 < 4; ++e2) v[e2] = (db ? S.o1[4 * g + e2] : S.o0[4 * g + e2]) * inv;
;             *(LAS f32x4*)(ostage + r32 * 272 + (32 * db + 8 * g + 4 * hi) * 4) = v;
;         }
;     asm volatile("s_waitcnt lgkmcnt(0)" ::: "memory");
; #pragma unroll
;     for (int i = 0; i < 4; ++i) {
;         const int row = i * 8 + (lane >> 3), c8 = lane & 7;
;         const f32x4 a = *(const LAS f32x4*)(ostage + row * 272 + c8 * 32), b = *(const LAS f32x4*)(ostage + row * 272 + c8 * 32 + 16);
;         const u32x4 gw = *(const u32x4*)(Grow + row * 64 + c8 * 8);
;         u32x4 w;
;         w.x = pk2(a[0] * bf_lo(gw.x), a[1] * bf_hi(gw.x)); w.y = pk2(a[2] * bf_lo(gw.y), a[3] * bf_hi(gw.y));
;         w.z = pk2(b[0] * bf_lo(gw.z), b[1] * bf_hi(gw.z)); w.w = pk2(b[2] * bf_lo(gw.w), b[3] * bf_hi(gw.w));
;         *(u32x4*)(Yrow + (size_t)row * 1024 + c8 * 8) = w;
;     }
;     asm volatile("s_waitcnt lgkmcnt(0)" ::: "memory");
.LBB0_596:
	v_mov_b32_e32 v0, v149
	s_nop 1
	v_permlane32_swap_b32_e32 v149, v0
	v_add_f32_e32 v0, v149, v0
	v_div_scale_f32 v2, s[0:1], v0, v0, 1.0
	v_rcp_f32_e32 v3, v2
	s_mulk_i32 s2, 0x2200
	s_add_i32 s0, s2, 0
	s_add_i32 s0, s0, 0x10800
	v_fma_f32 v4, -v2, v3, 1.0
	v_fmac_f32_e32 v3, v4, v3
	v_div_scale_f32 v4, vcc, 1.0, v0, 1.0
	v_mul_f32_e32 v5, v4, v3
	v_fma_f32 v6, -v2, v5, v4
	v_fmac_f32_e32 v5, v6, v3
	v_fma_f32 v2, -v2, v5, v4
	v_div_fmas_f32 v2, v2, v3, v5
	v_div_fixup_f32 v0, v2, v0, 1.0
	v_mul_u32_u24_e32 v6, 0x110, v124
	v_and_b32_e32 v7, 16, v125
	v_pk_mul_f32 v[2:3], v[32:33], v[0:1] op_sel_hi:[1,0]
	v_pk_mul_f32 v[4:5], v[34:35], v[0:1] op_sel_hi:[1,0]
	v_add3_u32 v6, s0, v6, v7
	ds_write_b128 v6, v[2:5]
	v_pk_mul_f32 v[2:3], v[36:37], v[0:1] op_sel_hi:[1,0]
	v_pk_mul_f32 v[4:5], v[38:39], v[0:1] op_sel_hi:[1,0]
	ds_write_b128 v6, v[2:5] offset:32
	v_pk_mul_f32 v[2:3], v[40:41], v[0:1] op_sel_hi:[1,0]
	v_pk_mul_f32 v[4:5], v[42:43], v[0:1] op_sel_hi:[1,0]
	ds_write_b128 v6, v[2:5] offset:64
	v_pk_mul_f32 v[2:3], v[44:45], v[0:1] op_sel_hi:[1,0]
	v_pk_mul_f32 v[4:5], v[46:47], v[0:1] op_sel_hi:[1,0]
	ds_write_b128 v6, v[2:5] offset:96
	v_pk_mul_f32 v[2:3], v[16:17], v[0:1] op_sel_hi:[1,0]
	v_pk_mul_f32 v[4:5], v[18:19], v[0:1] op_sel_hi:[1,0]
	ds_write_b128 v6, v[2:5] offset:128
	v_pk_mul_f32 v[2:3], v[20:21], v[0:1] op_sel_hi:[1,0]
	v_pk_mul_f32 v[4:5], v[22:23], v[0:1] op_sel_hi:[1,0]
	ds_write_b128 v6, v[2:5] offset:160
	v_pk_mul_f32 v[2:3], v[24:25], v[0:1] op_sel_hi:[1,0]
	v_pk_mul_f32 v[4:5], v[26:27], v[0:1] op_sel_hi:[1,0]
	v_and_b32_e32 v22, 7, v123
	ds_write_b128 v6, v[2:5] offset:192
	v_pk_mul_f32 v[2:3], v[28:29], v[0:1] op_sel_hi:[1,0]
	v_pk_mul_f32 v[4:5], v[30:31], v[0:1] op_sel_hi:[1,0]
	v_lshlrev_b32_e32 v0, 4, v22
	ds_write_b128 v6, v[2:5] offset:224
	v_lshl_add_u64 v[6:7], s[8:9], 0, v[0:1]
	v_lshl_add_u64 v[14:15], s[16:17], 0, v[0:1]
	v_lshlrev_b32_e32 v0, 7, v122
	s_waitcnt lgkmcnt(0)
	v_lshl_add_u64 v[2:3], v[6:7], 0, v[0:1]
	v_lshlrev_b32_e32 v0, 11, v122
	v_or_b32_e32 v18, 8, v122
	v_mov_b32_e32 v2, v166
	v_mov_b32_e32 v3, v167
	v_mov_b32_e32 v4, v168
	v_mov_b32_e32 v5, v169
	v_lshl_add_u64 v[16:17], v[14:15], 0, v[0:1]
	v_lshlrev_b32_e32 v0, 7, v18
	v_lshl_add_u64 v[8:9], v[6:7], 0, v[0:1]
	v_mov_b32_e32 v10, v170
	v_mov_b32_e32 v11, v171
	v_mov_b32_e32 v12, v172
	v_mov_b32_e32 v13, v173
	v_lshlrev_b32_e32 v0, 11, v18
	v_or_b32_e32 v23, 16, v122
	v_lshl_add_u64 v[38:39], v[14:15], 0, v[0:1]
	v_lshlrev_b32_e32 v0, 7, v23
	v_lshl_add_u64 v[8:9], v[6:7], 0, v[0:1]
	v_mov_b32_e32 v18, v174
	v_mov_b32_e32 v19, v175
	v_mov_b32_e32 v20, v176
	v_mov_b32_e32 v21, v177
	v_or_b32_e32 v50, 24, v122
	v_lshlrev_b32_e32 v0, 11, v23
	v_lshl_add_u64 v[40:41], v[14:15], 0, v[0:1]
	v_lshlrev_b32_e32 v0, 7, v50
	v_lshl_add_u64 v[6:7], v[6:7], 0, v[0:1]
	v_mov_b32_e32 v6, v180
	v_mov_b32_e32 v7, v181
	v_mov_b32_e32 v8, v182
	v_mov_b32_e32 v9, v183
	v_mul_u32_u24_e32 v0, 0x110, v122
	v_lshlrev_b32_e32 v22, 5, v22
	v_add3_u32 v0, s0, v22, v0
	ds_read_b128 v[22:25], v0
	ds_read_b128 v[26:29], v0 offset:16
	ds_read_b128 v[30:33], v0 offset:2176
	ds_read_b128 v[34:37], v0 offset:2192
	s_mov_b32 s86, s23
	s_mov_b32 s33, 0xc600000
	s_mov_b64 s[66:67], 0x2000
	v_readlane_b32 s11, v240, 47
	v_readlane_b32 s19, v240, 48
	s_waitcnt vmcnt(3)
	v_lshlrev_b32_e32 v42, 16, v2
	v_and_b32_e32 v43, 0xffff0000, v2
	v_lshlrev_b32_e32 v2, 16, v3
	v_and_b32_e32 v3, 0xffff0000, v3
	v_lshlrev_b32_e32 v44, 16, v4
	v_and_b32_e32 v45, 0xffff0000, v4
	v_lshlrev_b32_e32 v4, 16, v5
	v_and_b32_e32 v5, 0xffff0000, v5
	s_waitcnt lgkmcnt(3)
	v_pk_mul_f32 v[22:23], v[22:23], v[42:43]
	v_pk_mul_f32 v[24:25], v[24:25], v[2:3]
	s_waitcnt lgkmcnt(2)
	v_pk_mul_f32 v[26:27], v[26:27], v[44:45]
	v_pk_mul_f32 v[28:29], v[28:29], v[4:5]
	s_waitcnt vmcnt(2)
	v_lshlrev_b32_e32 v48, 16, v11
	v_cvt_pk_bf16_f32 v2, v22, v23
	v_cvt_pk_bf16_f32 v3, v24, v25
	v_cvt_pk_bf16_f32 v4, v26, v27
	v_cvt_pk_bf16_f32 v5, v28, v29
	v_and_b32_e32 v49, 0xffff0000, v11
	global_store_dwordx4 v[16:17], v[2:5], off
	v_lshlrev_b32_e32 v46, 16, v10
	v_and_b32_e32 v47, 0xffff0000, v10
	s_waitcnt lgkmcnt(1)
	v_pk_mul_f32 v[2:3], v[32:33], v[48:49]
	v_pk_mul_f32 v[30:31], v[30:31], v[46:47]
	v_cvt_pk_bf16_f32 v11, v2, v3
	v_lshlrev_b32_e32 v2, 16, v12
	v_and_b32_e32 v3, 0xffff0000, v12
	s_waitcnt lgkmcnt(0)
	v_pk_mul_f32 v[2:3], v[34:35], v[2:3]
	v_cvt_pk_bf16_f32 v10, v30, v31
	v_cvt_pk_bf16_f32 v12, v2, v3
	v_lshlrev_b32_e32 v2, 16, v13
	v_and_b32_e32 v3, 0xffff0000, v13
	v_pk_mul_f32 v[2:3], v[36:37], v[2:3]
	s_waitcnt vmcnt(2)
	v_lshlrev_b32_e32 v16, 16, v18
	v_cvt_pk_bf16_f32 v13, v2, v3
	ds_read_b128 v[2:5], v0 offset:4352
	global_store_dwordx4 v[38:39], v[10:13], off
	ds_read_b128 v[10:13], v0 offset:4368
	v_and_b32_e32 v17, 0xffff0000, v18
	s_waitcnt lgkmcnt(1)
	v_pk_mul_f32 v[2:3], v[2:3], v[16:17]
	v_lshlrev_b32_e32 v16, 16, v19
	v_and_b32_e32 v17, 0xffff0000, v19
	v_pk_mul_f32 v[4:5], v[4:5], v[16:17]
	v_cvt_pk_bf16_f32 v2, v2, v3
	v_cvt_pk_bf16_f32 v3, v4, v5
	v_lshlrev_b32_e32 v4, 16, v20
	v_and_b32_e32 v5, 0xffff0000, v20
	s_waitcnt lgkmcnt(0)
	v_pk_mul_f32 v[4:5], v[10:11], v[4:5]
	v_lshlrev_b32_e32 v10, 16, v21
	v_and_b32_e32 v11, 0xffff0000, v21
	v_pk_mul_f32 v[10:11], v[12:13], v[10:11]
	v_cvt_pk_bf16_f32 v4, v4, v5
	v_cvt_pk_bf16_f32 v5, v10, v11
	ds_read_b128 v[10:13], v0 offset:6528
	global_store_dwordx4 v[40:41], v[2:5], off
	ds_read_b128 v[2:5], v0 offset:6544
	s_waitcnt vmcnt(3)
	v_lshlrev_b32_e32 v16, 16, v6
	v_and_b32_e32 v17, 0xffff0000, v6
	s_waitcnt lgkmcnt(1)
	v_pk_mul_f32 v[10:11], v[10:11], v[16:17]
	v_lshlrev_b32_e32 v0, 11, v50
	v_cvt_pk_bf16_f32 v6, v10, v11
	v_lshlrev_b32_e32 v10, 16, v7
	v_and_b32_e32 v11, 0xffff0000, v7
	v_pk_mul_f32 v[10:11], v[12:13], v[10:11]
	s_nop 0
	v_cvt_pk_bf16_f32 v7, v10, v11
	v_lshlrev_b32_e32 v10, 16, v8
	v_and_b32_e32 v11, 0xffff0000, v8
	s_waitcnt lgkmcnt(0)
	v_pk_mul_f32 v[2:3], v[2:3], v[10:11]
	s_nop 0
	v_cvt_pk_bf16_f32 v8, v2, v3
	v_lshlrev_b32_e32 v2, 16, v9
	v_and_b32_e32 v3, 0xffff0000, v9
	v_pk_mul_f32 v[2:3], v[4:5], v[2:3]
	s_nop 0
	v_cvt_pk_bf16_f32 v9, v2, v3
	v_lshl_add_u64 v[2:3], v[14:15], 0, v[0:1]
	global_store_dwordx4 v[2:3], v[6:9], off
	s_waitcnt lgkmcnt(0)

; template <int MODE> ...
;     ...
;     bf16x8 qf[4];
; #pragma unroll
;     for (int d0 = 0; d0 < 4; ++d0) qf[d0] = *(const bf16x8*)(Qrow + r32 * 64 + d0 * 16 + hi * 8);
;     const int kkey = 8 * w + (lane >> 3), kch = (lane & 7) ^ ((kkey >> 1) & 7);
;     const int vkey = 8 * w + ((lane >> 2) & 7), vch = 4 * ((lane >> 5) & 1) + (lane & 3);
;     const bf16_t* kg = Kb + kkey * 64 + kch * 8;
;     const bf16_t* vg = Vb + vkey * 64 + vch * 8;
;     const unsigned ring0 = (unsigned)(unsigned long)ring;
;     const unsigned kdst = (unsigned)__builtin_amdgcn_readfirstlane(ring0 + w * 1024), vdst = kdst + 8192;
;     const float cq = (MODE == 1) ? tab[qpos0 + r32] : 0.f;
;     const float cfar = (MODE == 0) ? tab[256] : 0.f;
;     const unsigned vl = v_lane_off(lane);
;     St S; st_init(S);
;     asm volatile("" :: "v"(qf[0]), "v"(qf[1]), "v"(qf[2]), "v"(qf[3]));
;     constexpr bool REV = (MODE == 1);
;     ...
;     int s0 = 0, s1 = 16384, s2 = 32768;
; __device__ __forceinline__ void phase2(const Params& P, LAS unsigned char* lds, int tid, int lane, int wave) {
;     ...
;         for (int it = 0; it < 16; ++it) {
;             const int mode = it < 8, u = it & 7;
;             const int hc = 8 * u + wave;
;             const size_t qrow = (size_t)b * SEQ + hc * 32;
;             const size_t ho = (size_t)(b * 8 + h) * 2048 * 64;
;             const bf16_t* Qrow = (const bf16_t*)(P.ws + WS_SEG + (size_t)(mode ? 4 : 0) * SEG_STRIDE) + ho + (size_t)hc * 32 * 64;
;             const bf16_t* Grow = (const bf16_t*)(P.ws + WS_SEG + (size_t)(mode ? 7 : 3) * SEG_STRIDE) + ho + (size_t)hc * 32 * 64;
;             const bf16_t* Kb = (const bf16_t*)(P.ws + WS_SEG + (size_t)(mode ? 5 : 1) * SEG_STRIDE) + ho;
;             const bf16_t* Vb = (const bf16_t*)(P.ws + WS_SEG + (size_t)(mode ? 6 : 2) * SEG_STRIDE) + ho;
;             bf16_t* Yrow = (bf16_t*)(P.ws + WS_H) + qrow * 1024 + (mode ? 512 : 0) + h * 64;
;             if (mode) {
;                 att::super_unit<1>(Qrow, Kb, Vb, 0, 4 * u + 4, 0, (hc >> 1) + 1, hc * 32, c2p, Yrow, Grow, work, tid, lane);
;             } else {
;                 const int n = hc >> 1, lo = (n - 8) < 0 ? 0 : (n - 8), t0 = (4 * u - 8) < 0 ? 0 : (4 * u - 8);
;                 att::super_unit<0>(Qrow, Kb, Vb, t0, 4 * u + 4, lo, n + 1, hc * 32, rb2, Yrow, Grow, work, tid, lane);
.LBB0_598:
	s_and_b32 s2, s99, 7
	s_lshl_b32 s0, s2, 3
	s_add_i32 s0, s86, s0
	s_and_b32 s4, s21, 7
	s_lshr_b32 s6, s0, 1
	s_lshl_b32 s0, s4, 3
	s_add_i32 s40, s0, s86
	s_lshl_b32 s12, s40, 5
	s_cmp_lt_u32 s21, 8
	s_mov_b32 s1, 0x14a00000
	s_cselect_b32 s0, 0x10800000, 0
	s_cselect_b32 s5, s1, 0x4200000
	s_mov_b32 s1, 0x18c00000
	s_mov_b32 s41, s13
	s_cselect_b32 s3, 0x1ce00000, s33
	s_cselect_b32 s7, s1, 0x8400000
	s_cselect_b32 s10, 0x400, 0
	s_add_u32 s8, s29, s0
	s_addc_u32 s9, s98, 0
	s_lshl_b64 s[0:1], s[40:41], 12
	s_add_u32 s42, s8, s0
	s_addc_u32 s43, s9, s1
	s_add_u32 s3, s29, s3
	s_addc_u32 s9, s98, 0
	s_add_u32 s8, s3, s0
	s_addc_u32 s9, s9, s1
	s_add_u32 s36, s29, s5
	s_addc_u32 s37, s98, 0
	s_add_u32 s38, s29, s7
	s_addc_u32 s39, s98, 0
	s_lshl_b64 s[0:1], s[12:13], 11
	s_add_u32 s0, s11, s0
	s_addc_u32 s1, s19, s1
	s_add_u32 s0, s0, s10
	s_addc_u32 s1, s1, 0
	v_readlane_b32 s16, v240, 45
	v_readlane_b32 s17, v240, 46
	s_add_u32 s16, s0, s16
	s_addc_u32 s17, s1, s17
	s_cmp_gt_u32 s21, 7
	s_mov_b64 s[0:1], -1
	s_cbranch_scc0 .LBB0_634
	v_mov_b32_e32 v143, v120
	v_mov_b32_e32 v5, v1
	v_and_b32_e32 v144, 31, v143
	v_bfe_u32 v6, v143, 5, 1
	v_lshlrev_b32_e32 v0, 7, v144
	v_lshl_add_u64 v[2:3], s[42:43], 0, v[0:1]
	v_lshlrev_b32_e32 v4, 4, v6
	v_lshl_add_u64 v[2:3], v[2:3], 0, v[4:5]
	global_load_dwordx4 v[80:83], v[2:3], off
	global_load_dwordx4 v[84:87], v[2:3], off offset:32
	global_load_dwordx4 v[88:91], v[2:3], off offset:64
	global_load_dwordx4 v[92:95], v[2:3], off offset:96
	v_and_b32_e32 v235, 7, v143
	v_lshlrev_b32_e32 v235, 4, v235
	v_bfe_u32 v236, v143, 3, 3
	v_lshl_add_u32 v236, v236, 7, v235
	v_mov_b32_e32 v237, 0
	v_lshl_add_u64 v[236:237], s[8:9], 0, v[236:237]
	global_load_dwordx4 v[166:169], v[236:237], off
	global_load_dwordx4 v[170:173], v[236:237], off offset:1024
	global_load_dwordx4 v[174:177], v[236:237], off offset:2048
	global_load_dwordx4 v[180:183], v[236:237], off offset:3072
	s_lshl_b32 s3, s4, 2
	s_add_i32 s0, s3, -8
	s_cmp_gt_u32 s4, 1
	v_readfirstlane_b32 s4, v143
	v_and_b32_e32 v2, 32, v143
	v_lshlrev_b32_e32 v4, 3, v143
	s_cselect_b32 s44, s0, 0
	s_ashr_i32 s7, s4, 6
	v_bfe_u32 v142, v143, 3, 3
	v_and_or_b32 v2, v4, 24, v2
	s_lshl_b32 s4, s7, 3
	v_lshlrev_b32_e32 v4, 1, v2
	v_or_b32_e32 v2, s4, v142
	v_lshrrev_b32_e32 v7, 2, v143
	v_lshrrev_b32_e32 v11, 1, v2
	v_and_or_b32 v9, v7, 7, s4
	v_lshlrev_b32_e32 v8, 6, v2
	v_xor_b32_e32 v2, v11, v143
	v_lshlrev_b32_e32 v10, 6, v9
	v_ashrrev_i32_e32 v9, 31, v8
	v_lshlrev_b32_e32 v2, 4, v2
	v_mov_b32_e32 v3, v1
	s_lshl_b32 s5, s7, 10
	v_ashrrev_i32_e32 v11, 31, v10
	v_lshl_add_u64 v[8:9], v[8:9], 1, s[36:37]
	v_and_b32_e32 v2, 0x70, v2
	s_mov_b32 s1, s13
	ds_read_b32 v145, v1 offset:17664
	s_lshl_b32 s0, s44, 13
	s_add_i32 s4, s5, 0
	v_lshl_add_u64 v[10:11], v[10:11], 1, s[38:39]
	v_lshl_add_u64 v[2:3], v[8:9], 0, v[2:3]
	s_add_i32 s24, s4, 0x4800
	v_lshl_add_u64 v[4:5], v[10:11], 0, v[4:5]
	v_lshl_add_u64 v[8:9], v[2:3], 0, s[0:1]
	s_add_i32 s25, s4, 0x6800
	s_add_i32 s15, s3, 4
	s_mov_b32 s5, m0
	s_mov_b32 m0, s24
	s_nop 0
	global_load_lds_dwordx4 v[8:9], off
	s_mov_b32 m0, s5
	v_lshl_add_u64 v[8:9], v[4:5], 0, s[0:1]
	s_mov_b32 s0, m0
	s_mov_b32 m0, s25
	s_nop 0
	global_load_lds_dwordx4 v[8:9], off
	s_mov_b32 m0, s0
	s_or_b32 s5, s44, 1
	s_cmp_ge_u32 s5, s15
	s_mov_b64 s[0:1], -1
	s_cbranch_scc0 .LBB0_601
	s_waitcnt vmcnt(0) lgkmcnt(0)
	s_barrier
	s_cbranch_execnz .LBB0_603
	s_branch .LBB0_602

; #define LAS __attribute__((address_space(3)))
; __device__ __forceinline__ unsigned pk2(float lo, float hi) { f32x2_t v = {lo, hi}; bf16x2_t b = __builtin_convertvector(v, bf16x2_t); return __builtin_bit_cast(unsigned, b); }
; __device__ __forceinline__ float bf_lo(unsigned w) { return __uint_as_float(w << 16); }
; __device__ __forceinline__ float bf_hi(unsigned w) { return __uint_as_float(w & 0xffff0000u); }
; __device__ __forceinline__ void finish(St& S, bf16_t* Yrow, const bf16_t* __restrict__ Grow, LAS unsigned char* ostage, int lane) {
;     const int r32 = lane & 31, hi = lane >> 5;
;     const float inv = 1.0f / xhalf_sum(S.l);
; #pragma unroll
;     for (int db = 0; db < 2; ++db)
; #pragma unroll
;         for (int g = 0; g < 4; ++g) {
;             f32x4 v;
; #pragma unroll
;             for (int e2 = 0; e2 < 4; ++e2) v[e2] = (db ? S.o1[4 * g + e2] : S.o0[4 * g + e2]) * inv;
;             *(LAS f32x4*)(ostage + r32 * 272 + (32 * db + 8 * g + 4 * hi) * 4) = v;
;         }
;     asm volatile("s_waitcnt lgkmcnt(0)" ::: "memory");
; #pragma unroll
;     for (int i = 0; i < 4; ++i) {
;         const int row = i * 8 + (lane >> 3), c8 = lane & 7;
;         const f32x4 a = *(const LAS f32x4*)(ostage + row * 272 + c8 * 32), b = *(const LAS f32x4*)(ostage + row * 272 + c8 * 32 + 16);
;         const u32x4 gw = *(const u32x4*)(Grow + row * 64 + c8 * 8);
;         u32x4 w;
;         w.x = pk2(a[0] * bf_lo(gw.x), a[1] * bf_hi(gw.x)); w.y = pk2(a[2] * bf_lo(gw.y), a[3] * bf_hi(gw.y));
;         w.z = pk2(b[0] * bf_lo(gw.z), b[1] * bf_hi(gw.z)); w.w = pk2(b[2] * bf_lo(gw.w), b[3] * bf_hi(gw.w));
;         *(u32x4*)(Yrow + (size_t)row * 1024 + c8 * 8) = w;
;     }
;     asm volatile("s_waitcnt lgkmcnt(0)" ::: "memory");
.LBB0_633:
	v_mov_b32_e32 v0, v150
	s_nop 1
	v_permlane32_swap_b32_e32 v150, v0
	v_add_f32_e32 v0, v150, v0
	v_div_scale_f32 v2, s[0:1], v0, v0, 1.0
	v_rcp_f32_e32 v3, v2
	s_mulk_i32 s7, 0x2200
	s_add_i32 s0, s7, 0
	s_add_i32 s0, s0, 0x10800
	v_fma_f32 v4, -v2, v3, 1.0
	v_fmac_f32_e32 v3, v4, v3
	v_div_scale_f32 v4, vcc, 1.0, v0, 1.0
	v_mul_f32_e32 v5, v4, v3
	v_fma_f32 v6, -v2, v5, v4
	v_fmac_f32_e32 v5, v6, v3
	v_fma_f32 v2, -v2, v5, v4
	v_div_fmas_f32 v2, v2, v3, v5
	v_div_fixup_f32 v0, v2, v0, 1.0
	v_mul_u32_u24_e32 v6, 0x110, v144
	v_and_b32_e32 v7, 16, v146
	v_pk_mul_f32 v[2:3], v[32:33], v[0:1] op_sel_hi:[1,0]
	v_pk_mul_f32 v[4:5], v[34:35], v[0:1] op_sel_hi:[1,0]
	v_add3_u32 v6, s0, v6, v7
	ds_write_b128 v6, v[2:5]
	v_pk_mul_f32 v[2:3], v[36:37], v[0:1] op_sel_hi:[1,0]
	v_pk_mul_f32 v[4:5], v[38:39], v[0:1] op_sel_hi:[1,0]
	ds_write_b128 v6, v[2:5] offset:32
	v_pk_mul_f32 v[2:3], v[40:41], v[0:1] op_sel_hi:[1,0]
	v_pk_mul_f32 v[4:5], v[42:43], v[0:1] op_sel_hi:[1,0]
	ds_write_b128 v6, v[2:5] offset:64
	v_pk_mul_f32 v[2:3], v[44:45], v[0:1] op_sel_hi:[1,0]
	v_pk_mul_f32 v[4:5], v[46:47], v[0:1] op_sel_hi:[1,0]
	ds_write_b128 v6, v[2:5] offset:96
	v_pk_mul_f32 v[2:3], v[16:17], v[0:1] op_sel_hi:[1,0]
	v_pk_mul_f32 v[4:5], v[18:19], v[0:1] op_sel_hi:[1,0]
	ds_write_b128 v6, v[2:5] offset:128
	v_pk_mul_f32 v[2:3], v[20:21], v[0:1] op_sel_hi:[1,0]
	v_pk_mul_f32 v[4:5], v[22:23], v[0:1] op_sel_hi:[1,0]
	ds_write_b128 v6, v[2:5] offset:160
	v_pk_mul_f32 v[2:3], v[24:25], v[0:1] op_sel_hi:[1,0]
	v_pk_mul_f32 v[4:5], v[26:27], v[0:1] op_sel_hi:[1,0]
	v_and_b32_e32 v22, 7, v143
	ds_write_b128 v6, v[2:5] offset:192
	v_pk_mul_f32 v[2:3], v[28:29], v[0:1] op_sel_hi:[1,0]
	v_pk_mul_f32 v[4:5], v[30:31], v[0:1] op_sel_hi:[1,0]
	v_lshlrev_b32_e32 v0, 4, v22
	ds_write_b128 v6, v[2:5] offset:224
	v_lshl_add_u64 v[6:7], s[8:9], 0, v[0:1]
	v_lshl_add_u64 v[14:15], s[16:17], 0, v[0:1]
	v_lshlrev_b32_e32 v0, 7, v142
	s_waitcnt lgkmcnt(0)
	v_lshl_add_u64 v[2:3], v[6:7], 0, v[0:1]
	v_lshlrev_b32_e32 v0, 11, v142
	v_or_b32_e32 v18, 8, v142
	v_mov_b32_e32 v2, v166
	v_mov_b32_e32 v3, v167
	v_mov_b32_e32 v4, v168
	v_mov_b32_e32 v5, v169
	v_lshl_add_u64 v[16:17], v[14:15], 0, v[0:1]
	v_lshlrev_b32_e32 v0, 7, v18
	v_lshl_add_u64 v[8:9], v[6:7], 0, v[0:1]
	v_mov_b32_e32 v10, v170
	v_mov_b32_e32 v11, v171
	v_mov_b32_e32 v12, v172
	v_mov_b32_e32 v13, v173
	v_lshlrev_b32_e32 v0, 11, v18
	v_or_b32_e32 v23, 16, v142
	v_lshl_add_u64 v[38:39], v[14:15], 0, v[0:1]
	v_lshlrev_b32_e32 v0, 7, v23
	v_lshl_add_u64 v[8:9], v[6:7], 0, v[0:1]
	v_mov_b32_e32 v18, v174
	v_mov_b32_e32 v19, v175
	v_mov_b32_e32 v20, v176
	v_mov_b32_e32 v21, v177
	v_or_b32_e32 v50, 24, v142
	v_lshlrev_b32_e32 v0, 11, v23
	v_lshl_add_u64 v[40:41], v[14:15], 0, v[0:1]
	v_lshlrev_b32_e32 v0, 7, v50
	v_lshl_add_u64 v[6:7], v[6:7], 0, v[0:1]
	v_mov_b32_e32 v6, v180
	v_mov_b32_e32 v7, v181
	v_mov_b32_e32 v8, v182
	v_mov_b32_e32 v9, v183
	v_mul_u32_u24_e32 v0, 0x110, v142
	v_lshlrev_b32_e32 v22, 5, v22
	v_add3_u32 v0, s0, v22, v0
	ds_read_b128 v[22:25], v0
	ds_read_b128 v[26:29], v0 offset:16
	ds_read_b128 v[30:33], v0 offset:2176
	ds_read_b128 v[34:37], v0 offset:2192
	s_mov_b64 s[0:1], 0
	s_waitcnt vmcnt(3)
	v_lshlrev_b32_e32 v42, 16, v2
	v_and_b32_e32 v43, 0xffff0000, v2
	v_lshlrev_b32_e32 v2, 16, v3
	v_and_b32_e32 v3, 0xffff0000, v3
	v_lshlrev_b32_e32 v44, 16, v4
	v_and_b32_e32 v45, 0xffff0000, v4
	v_lshlrev_b32_e32 v4, 16, v5
	v_and_b32_e32 v5, 0xffff0000, v5
	s_waitcnt lgkmcnt(3)
	v_pk_mul_f32 v[22:23], v[22:23], v[42:43]
	v_pk_mul_f32 v[24:25], v[24:25], v[2:3]
	s_waitcnt lgkmcnt(2)
	v_pk_mul_f32 v[26:27], v[26:27], v[44:45]
	v_pk_mul_f32 v[28:29], v[28:29], v[4:5]
	s_waitcnt vmcnt(2)
	v_lshlrev_b32_e32 v48, 16, v11
	v_cvt_pk_bf16_f32 v2, v22, v23
	v_cvt_pk_bf16_f32 v3, v24, v25
	v_cvt_pk_bf16_f32 v4, v26, v27
	v_cvt_pk_bf16_f32 v5, v28, v29
	v_and_b32_e32 v49, 0xffff0000, v11
	global_store_dwordx4 v[16:17], v[2:5], off
	v_lshlrev_b32_e32 v46, 16, v10
	v_and_b32_e32 v47, 0xffff0000, v10
	s_waitcnt lgkmcnt(1)
	v_pk_mul_f32 v[2:3], v[32:33], v[48:49]
	v_pk_mul_f32 v[30:31], v[30:31], v[46:47]
	v_cvt_pk_bf16_f32 v11, v2, v3
	v_lshlrev_b32_e32 v2, 16, v12
	v_and_b32_e32 v3, 0xffff0000, v12
	s_waitcnt lgkmcnt(0)
	v_pk_mul_f32 v[2:3], v[34:35], v[2:3]
	v_cvt_pk_bf16_f32 v10, v30, v31
	v_cvt_pk_bf16_f32 v12, v2, v3
	v_lshlrev_b32_e32 v2, 16, v13
	v_and_b32_e32 v3, 0xffff0000, v13
	v_pk_mul_f32 v[2:3], v[36:37], v[2:3]
	s_waitcnt vmcnt(2)
	v_lshlrev_b32_e32 v16, 16, v18
	v_cvt_pk_bf16_f32 v13, v2, v3
	ds_read_b128 v[2:5], v0 offset:4352
	global_store_dwordx4 v[38:39], v[10:13], off
	ds_read_b128 v[10:13], v0 offset:4368
	v_and_b32_e32 v17, 0xffff0000, v18
	s_waitcnt lgkmcnt(1)
	v_pk_mul_f32 v[2:3], v[2:3], v[16:17]
	v_lshlrev_b32_e32 v16, 16, v19
	v_and_b32_e32 v17, 0xffff0000, v19
	v_pk_mul_f32 v[4:5], v[4:5], v[16:17]
	v_cvt_pk_bf16_f32 v2, v2, v3
	v_cvt_pk_bf16_f32 v3, v4, v5
	v_lshlrev_b32_e32 v4, 16, v20
	v_and_b32_e32 v5, 0xffff0000, v20
	s_waitcnt lgkmcnt(0)
	v_pk_mul_f32 v[4:5], v[10:11], v[4:5]
	v_lshlrev_b32_e32 v10, 16, v21
	v_and_b32_e32 v11, 0xffff0000, v21
	v_pk_mul_f32 v[10:11], v[12:13], v[10:11]
	v_cvt_pk_bf16_f32 v4, v4, v5
	v_cvt_pk_bf16_f32 v5, v10, v11
	ds_read_b128 v[10:13], v0 offset:6528
	global_store_dwordx4 v[40:41], v[2:5], off
	ds_read_b128 v[2:5], v0 offset:6544
	s_waitcnt vmcnt(3)
	v_lshlrev_b32_e32 v16, 16, v6
	v_and_b32_e32 v17, 0xffff0000, v6
	s_waitcnt lgkmcnt(1)
	v_pk_mul_f32 v[10:11], v[10:11], v[16:17]
	v_lshlrev_b32_e32 v0, 11, v50
	v_cvt_pk_bf16_f32 v6, v10, v11
	v_lshlrev_b32_e32 v10, 16, v7
	v_and_b32_e32 v11, 0xffff0000, v7
	v_pk_mul_f32 v[10:11], v[12:13], v[10:11]
	s_nop 0
	v_cvt_pk_bf16_f32 v7, v10, v11
	v_lshlrev_b32_e32 v10, 16, v8
	v_and_b32_e32 v11, 0xffff0000, v8
	s_waitcnt lgkmcnt(0)
	v_pk_mul_f32 v[2:3], v[2:3], v[10:11]
	s_nop 0
	v_cvt_pk_bf16_f32 v8, v2, v3
	v_lshlrev_b32_e32 v2, 16, v9
	v_and_b32_e32 v3, 0xffff0000, v9
	v_pk_mul_f32 v[2:3], v[4:5], v[2:3]
	s_nop 0
	v_cvt_pk_bf16_f32 v9, v2, v3
	v_lshl_add_u64 v[2:3], v[14:15], 0, v[0:1]
	global_store_dwordx4 v[2:3], v[6:9], off
	s_waitcnt lgkmcnt(0)
; __device__ __forceinline__ int crow(int r, int hi) { return (r & 3) + 8 * (r >> 2) + 4 * hi; }
; __device__ __forceinline__ unsigned v_lane_off(int lane) { return (unsigned)((4 * (lane >> 5) + ((lane & 15) >> 2)) * 64 + ((lane >> 4) & 1) * 32 + (lane & 3) * 8); }
; template <int MODE>
; __device__ __forceinline__ void step64(St& S, const bf16x8 (&qf)[4], int t, int qpos0, bool diag, bool first, float cq, float cfar, const LAS float* tab,
;                                        const LAS unsigned char* buf, unsigned vaddr, int r32, int hi) {
;     ...
;     if (MODE == 1 && diag) {
;         const int qrel = qpos0 - t * 64 + r32;
; #pragma unroll
;         for (int r = 0; r < 16; ++r) { if (crow(r, hi) > qrel) sa[r] = -1e30f; if (crow(r, hi) + 32 > qrel) sb[r] = -1e30f; }
; template <int MODE> ...
;     ...
;     bf16x8 qf[4];
; #pragma unroll
;     for (int d0 = 0; d0 < 4; ++d0) qf[d0] = *(const bf16x8*)(Qrow + r32 * 64 + d0 * 16 + hi * 8);
;     const int kkey = 8 * w + (lane >> 3), kch = (lane & 7) ^ ((kkey >> 1) & 7);
;     const int vkey = 8 * w + ((lane >> 2) & 7), vch = 4 * ((lane >> 5) & 1) + (lane & 3);
;     const bf16_t* kg = Kb + kkey * 64 + kch * 8;
;     const bf16_t* vg = Vb + vkey * 64 + vch * 8;
;     const unsigned ring0 = (unsigned)(unsigned long)ring;
;     const unsigned kdst = (unsigned)__builtin_amdgcn_readfirstlane(ring0 + w * 1024), vdst = kdst + 8192;
;     const float cq = (MODE == 1) ? tab[qpos0 + r32] : 0.f;
;     const float cfar = (MODE == 0) ? tab[256] : 0.f;
;     const unsigned vl = v_lane_off(lane);
;     St S; st_init(S);
;     asm volatile("" :: "v"(qf[0]), "v"(qf[1]), "v"(qf[2]), "v"(qf[3]));
;     constexpr bool REV = (MODE == 1);
;     ...
;     int s0 = 0, s1 = 16384, s2 = 32768;
;     glds16(kg + (size_t)SU_T(T0) * 4096, kdst + s0); glds16(vg + (size_t)SU_T(T0) * 4096, vdst + s0);
;     if (T0 + 1 < T1) { glds16(kg + (size_t)SU_T(T0 + 1) * 4096, kdst + s1); glds16(vg + (size_t)SU_T(T0 + 1) * 4096, vdst + s1);
;                        asm volatile("s_waitcnt vmcnt(2) lgkmcnt(0)\n\ts_barrier" ::: "memory"); }
;     else             { asm volatile("s_waitcnt vmcnt(0) lgkmcnt(0)\n\ts_barrier" ::: "memory"); }
.LBB0_634:
	s_and_b64 vcc, exec, s[0:1]
	s_cbranch_vccz .LBB0_597
	v_mov_b32_e32 v123, v120
	v_mov_b32_e32 v5, v1
	v_and_b32_e32 v124, 31, v123
	v_bfe_u32 v6, v123, 5, 1
	v_lshlrev_b32_e32 v0, 7, v124
	v_lshl_add_u64 v[2:3], s[42:43], 0, v[0:1]
	v_lshlrev_b32_e32 v4, 4, v6
	v_lshl_add_u64 v[2:3], v[2:3], 0, v[4:5]
	global_load_dwordx4 v[80:83], v[2:3], off
	global_load_dwordx4 v[84:87], v[2:3], off offset:32
	global_load_dwordx4 v[88:91], v[2:3], off offset:64
	global_load_dwordx4 v[92:95], v[2:3], off offset:96
	v_and_b32_e32 v235, 7, v123
	v_lshlrev_b32_e32 v235, 4, v235
	v_bfe_u32 v236, v123, 3, 3
	v_lshl_add_u32 v236, v236, 7, v235
	v_mov_b32_e32 v237, 0
	v_lshl_add_u64 v[236:237], s[8:9], 0, v[236:237]
	global_load_dwordx4 v[166:169], v[236:237], off
	global_load_dwordx4 v[170:173], v[236:237], off offset:1024
	global_load_dwordx4 v[174:177], v[236:237], off offset:2048
	global_load_dwordx4 v[180:183], v[236:237], off offset:3072
	s_lshl_b32 s4, s21, 14
	s_lshl_b32 s1, s12, 2
	s_mov_b32 s3, s13
	s_or_b32 s2, s4, 0x3000
	v_readfirstlane_b32 s10, v123
	s_sub_i32 s15, 0, s6
	s_add_i32 s1, s1, 0
	v_lshrrev_b32_e32 v8, 3, v123
	v_bfe_u32 v9, v123, 2, 2
	v_lshlrev_b32_e32 v10, 1, v123
	s_lshl_b64 s[6:7], s[2:3], 1
	v_lshrrev_b32_e32 v125, 1, v123
	s_ashr_i32 s2, s10, 6
	v_bfe_u32 v122, v123, 3, 3
	v_lshlrev_b32_e32 v5, 3, v123
	v_lshl_add_u32 v12, v124, 2, s1
	v_and_or_b32 v8, v8, 4, v9
	v_and_b32_e32 v9, 32, v10
	v_bitop3_b32 v10, v6, v125, 7 bitop3:0x78
	s_lshl_b32 s1, s2, 3
	v_lshrrev_b32_e32 v2, 2, v123
	v_bfe_u32 v11, v123, 1, 3
	v_and_b32_e32 v5, 24, v5
	v_lshlrev_b32_e32 v8, 6, v8
	v_lshl_or_b32 v143, v10, 4, v0
	v_or_b32_e32 v10, s1, v122
	v_bitop3_b32 v13, v6, v11, 2 bitop3:0x36
	v_bitop3_b32 v14, v6, v11, 4 bitop3:0x36
	v_bitop3_b32 v11, v6, v11, 6 bitop3:0x36
	v_lshlrev_b32_e32 v16, 2, v6
	v_and_or_b32 v6, v123, 32, v5
	v_and_or_b32 v2, v2, 7, s1
	v_or3_b32 v147, v5, v9, v8
	v_lshrrev_b32_e32 v5, 1, v10
	v_lshlrev_b32_e32 v8, 6, v10
	v_lshlrev_b32_e32 v10, 6, v2
	v_xor_b32_e32 v2, v5, v123
	v_lshl_or_b32 v146, v11, 4, v0
	v_ashrrev_i32_e32 v9, 31, v8
	v_ashrrev_i32_e32 v11, 31, v10
	v_lshlrev_b32_e32 v2, 4, v2
	v_mov_b32_e32 v3, v1
	v_mov_b32_e32 v7, v1
	s_mov_b32 s5, s13
	s_bitset1_b32 s4, 13
	s_lshl_b32 s3, s2, 10
	v_lshlrev_b32_e32 v6, 1, v6
	v_lshl_add_u64 v[8:9], v[8:9], 1, s[36:37]
	v_lshl_add_u64 v[10:11], v[10:11], 1, s[38:39]
	v_and_b32_e32 v2, 0x70, v2
	s_lshl_b64 s[4:5], s[4:5], 1
	s_add_i32 s1, s3, 0
	v_lshl_add_u64 v[6:7], v[10:11], 0, v[6:7]
	v_lshl_add_u64 v[2:3], v[8:9], 0, v[2:3]
	ds_read_b32 v142, v12
	v_lshl_or_b32 v144, v13, 4, v0
	v_lshl_or_b32 v145, v14, 4, v0
	s_add_i32 s20, s1, 0x4800
	v_lshl_add_u64 v[10:11], v[6:7], 0, s[4:5]
	v_lshl_add_u64 v[12:13], v[2:3], 0, s[6:7]
	v_lshl_add_u64 v[14:15], v[2:3], 0, s[4:5]
	s_add_i32 s3, s1, 0x6800
	v_lshl_add_u64 v[8:9], v[6:7], 0, s[6:7]
	s_lshr_b32 s28, s40, 1
	s_add_i32 s10, s1, 0x8800
	s_add_i32 s1, s1, 0xa800
	v_or_b32_e32 v0, 32, v16
	v_or_b32_e32 v17, 33, v16
	v_or_b32_e32 v5, 2, v16
	v_or_b32_e32 v18, 42, v16
	v_or_b32_e32 v19, 11, v16
	v_or_b32_e32 v20, 43, v16
	v_or_b32_e32 v21, 16, v16
	v_or_b32_e32 v22, 48, v16
	v_or_b32_e32 v23, 17, v16
	s_mov_b32 s4, m0
	s_mov_b32 m0, s20
	s_nop 0
	global_load_lds_dwordx4 v[12:13], off
	s_mov_b32 m0, s4
	v_or_b32_e32 v12, 40, v16
	s_mov_b32 s4, m0
	s_mov_b32 m0, s3
	s_nop 0
	global_load_lds_dwordx4 v[8:9], off
	s_mov_b32 m0, s4
	v_or_b32_e32 v8, 34, v16
	s_mov_b32 s4, m0
	s_mov_b32 m0, s10
	s_nop 0
	global_load_lds_dwordx4 v[14:15], off
	s_mov_b32 m0, s4
	v_or_b32_e32 v14, 41, v16
	s_mov_b32 s4, m0
	s_mov_b32 m0, s1
	s_nop 0
	global_load_lds_dwordx4 v[10:11], off
	s_mov_b32 m0, s4
	s_lshl_b32 s1, s28, 6
	s_sub_i32 s1, s12, s1
	v_or_b32_e32 v15, 10, v16
	v_or_b32_e32 v37, s1, v124
	s_waitcnt vmcnt(2) lgkmcnt(0)
	s_barrier
	v_or_b32_e32 v9, 3, v16
	v_or_b32_e32 v10, 35, v16
	v_or_b32_e32 v11, 8, v16
	v_or_b32_e32 v13, 9, v16
	v_or_b32_e32 v24, 49, v16
	v_or_b32_e32 v25, 18, v16
	v_or_b32_e32 v26, 50, v16
	v_or_b32_e32 v27, 19, v16
	v_or_b32_e32 v28, 51, v16
	v_or_b32_e32 v29, 24, v16
	v_or_b32_e32 v30, 56, v16
	v_or_b32_e32 v31, 25, v16
	v_or_b32_e32 v32, 57, v16
	v_or_b32_e32 v33, 26, v16
	v_or_b32_e32 v34, 58, v16
	v_or_b32_e32 v35, 27, v16
	v_or_b32_e32 v36, 59, v16
	v_cmp_gt_i32_e64 s[56:57], v14, v37
	v_cmp_gt_i32_e64 s[58:59], v15, v37
	v_mov_b32_e32 v14, v1
	v_mov_b32_e32 v15, v1
	s_mov_b32 s23, s86
	s_lshl_b32 s33, s21, 2
	v_cmp_gt_i32_e64 s[34:35], v16, v37
	v_cmp_gt_i32_e64 s[36:37], v0, v37
	v_cmp_lt_i32_e64 s[38:39], v16, v37
	v_cmp_gt_i32_e64 s[40:41], v17, v37
	v_cmp_gt_i32_e64 s[42:43], v5, v37
	v_cmp_gt_i32_e64 s[44:45], v8, v37
	v_cmp_gt_i32_e64 s[46:47], v9, v37
	v_cmp_gt_i32_e64 s[48:49], v10, v37
	v_cmp_gt_i32_e64 s[50:51], v11, v37
	v_cmp_gt_i32_e64 s[52:53], v12, v37
	v_cmp_gt_i32_e64 s[54:55], v13, v37
	v_cmp_gt_i32_e64 s[60:61], v18, v37
	v_cmp_gt_i32_e64 s[62:63], v19, v37
	v_cmp_gt_i32_e64 s[64:65], v20, v37
	v_cmp_gt_i32_e64 s[66:67], v21, v37
	v_cmp_gt_i32_e64 s[68:69], v22, v37
	v_cmp_gt_i32_e64 s[70:71], v23, v37
	v_cmp_gt_i32_e64 s[72:73], v24, v37
	v_cmp_gt_i32_e64 s[74:75], v25, v37
	v_cmp_gt_i32_e64 s[76:77], v26, v37
	v_cmp_gt_i32_e64 s[78:79], v27, v37
	v_cmp_gt_i32_e64 s[80:81], v28, v37
	v_cmp_gt_i32_e64 s[82:83], v29, v37
	v_cmp_gt_i32_e64 s[84:85], v30, v37
	v_cmp_gt_i32_e64 s[86:87], v31, v37
	v_cmp_gt_i32_e64 s[88:89], v32, v37
	v_cmp_gt_i32_e64 s[90:91], v33, v37
	v_cmp_gt_i32_e64 s[92:93], v34, v37
	v_cmp_gt_i32_e64 s[94:95], v35, v37
	v_cmp_gt_i32_e64 s[96:97], v36, v37
	v_lshl_add_u64 v[116:117], v[6:7], 0, s[30:31]
	v_lshl_add_u64 v[118:119], v[2:3], 0, s[30:31]
	v_add_u32_e32 v148, s14, v4
	v_mov_b32_e32 v0, v1
	v_mov_b32_e32 v2, v1
	v_mov_b32_e32 v3, v1
	v_mov_b32_e32 v4, v1
	v_mov_b32_e32 v5, v1
	v_mov_b32_e32 v6, v1
	v_mov_b32_e32 v7, v1
	v_mov_b32_e32 v8, v1
	v_mov_b32_e32 v9, v1
	v_mov_b32_e32 v10, v1
	v_mov_b32_e32 v11, v1
	v_mov_b32_e32 v12, v1
	v_mov_b32_e32 v13, v1
	v_mov_b64_e32 v[30:31], v[14:15]
	v_mov_b64_e32 v[46:47], v[14:15]
	s_mov_b32 s0, 0
	s_mov_b32 s19, 2
	s_add_i32 s33, s33, 4
	v_mov_b32_e32 v150, 0
	s_mov_b32 s12, 0x8000
	s_movk_i32 s10, 0x4000
	s_mov_b32 s1, s18
	v_mov_b32_e32 v149, 0
	v_mov_b64_e32 v[28:29], v[12:13]
	v_mov_b64_e32 v[26:27], v[10:11]
	v_mov_b64_e32 v[24:25], v[8:9]
	v_mov_b64_e32 v[22:23], v[6:7]
	v_mov_b64_e32 v[20:21], v[4:5]
	v_mov_b64_e32 v[18:19], v[2:3]
	v_mov_b64_e32 v[16:17], v[0:1]
	v_mov_b64_e32 v[44:45], v[12:13]
	v_mov_b64_e32 v[42:43], v[10:11]
	v_mov_b64_e32 v[40:41], v[8:9]
	v_mov_b64_e32 v[38:39], v[6:7]
	v_mov_b64_e32 v[36:37], v[4:5]
	v_mov_b64_e32 v[34:35], v[2:3]
	v_mov_b64_e32 v[32:33], v[0:1]
